# GP1+FO1 on MM1+PL1+PW1 R0=32768: weight-product unit: norm-gain load issued before the compute loop; both fill passes' loads in flight together
# speedup vs baseline: 1.0061x; 1.0022x over previous
; #define LAS __attribute__((address_space(3)))
; __device__ void p_weights_prod(const Args& a, LAS unsigned char* lds) {
;     ...
;     for (int u = blockIdx.x; u < 256; u += gridDim.x) {
;         const int l = u >> 7, g = (u >> 5) & 3, kblk = u & 31, pn = 7 + g;
;         __syncthreads();
;         {
;             const int rr = tid >> 4, c8 = (tid & 15) * 8;
;             const float* src = a.w_in + (size_t)l * DM * INW + (size_t)(kblk * 32 + rr) * INW + 1280 + g * 128 + c8;
;             const f32x4* msrc = (const f32x4*)(MM + (size_t)(l * 4 + g) * 128 * 256) + tid;
;             f32x4 mreg[16];
; #pragma unroll
;             for (int j = 0; j < 16; ++j) mreg[j] = msrc[j * NTHREADS];
;             *(LAS f32x4*)(wt + rr * 128 + c8) = *(const f32x4*)src; *(LAS f32x4*)(wt + rr * 128 + c8 + 4) = *(const f32x4*)(src + 4);
; #pragma unroll
;             for (int j = 0; j < 16; ++j) ((LAS f32x4*)mmt)[tid + j * NTHREADS] = mreg[j];
;         }
.LBB0_86:
.LBB0_87:
	v_readfirstlane_b32 s100, v0
	s_nop 3
	s_cmp_ge_u32 s100, 0x100
	s_cbranch_scc1 .Lpw_x
	v_mov_b32_e32 v8, v0
	v_lshlrev_b32_e32 v10, 4, v8
	s_load_dword s9, s[0:1], 0x60
	s_add_u32 s6, s40, 0x1fb00000
	v_lshlrev_b32_e32 v1, 1, v8
	v_and_b32_e32 v2, 0x90, v10
	s_movk_i32 s3, 0x6c
	v_lshlrev_b32_e32 v3, 3, v8
	v_ashrrev_i32_e32 v9, 31, v8
	s_addc_u32 s7, s41, 0
	v_and_or_b32 v2, v1, s3, v2
	v_ashrrev_i32_e32 v11, 6, v8
	v_ashrrev_i32_e32 v1, 4, v8
	v_and_b32_e32 v4, 0x78, v3
	v_lshl_add_u64 v[6:7], v[8:9], 4, s[40:41]
	s_mov_b64 s[4:5], 0x20a00000
	v_and_b32_e32 v8, 63, v8
	v_lshl_add_u64 v[6:7], v[6:7], 0, s[4:5]
	v_lshlrev_b32_e32 v3, 9, v1
	v_lshlrev_b32_e32 v9, 2, v4
	v_add_u32_e32 v24, 0, v10
	s_add_u32 s4, s0, 0x60
	v_lshl_add_u32 v8, v8, 4, 0
	v_mov_b32_e32 v5, 0
	s_mov_b32 s11, 0
	v_add3_u32 v3, 0, v3, v9
	s_movk_i32 s3, 0x4000
	v_add_u32_e32 v25, 0x4000, v24
	v_lshl_add_u32 v26, v11, 11, 0
	v_lshlrev_b32_e32 v27, 2, v11
	s_addc_u32 s5, s1, 0
	s_mov_b32 s14, 0x14000
	v_add_u32_e32 v28, 0x14000, v24
	s_mov_b32 s15, 0x16000
	v_add_u32_e32 v29, 0x16000, v24
	s_mov_b32 s33, 0x18000
	v_add_u32_e32 v30, 0x18000, v24
	s_mov_b32 s34, 0x1a000
	v_add_u32_e32 v31, 0x1a000, v24
	s_mov_b32 s35, 0x1c000
	v_add_u32_e32 v32, 0x1c000, v24
	s_mov_b32 s36, 0x1e000
	v_add_u32_e32 v33, 0x1e000, v24
	v_add_u32_e32 v34, 0x20000, v24
	v_add_u32_e32 v35, 0x22000, v24
	v_add_u32_e32 v36, 0x4000, v8
	s_movk_i32 s37, 0x2400
	s_movk_i32 s44, 0x2000
	s_movk_i32 s45, 0x6000
	s_mov_b32 s46, 0x8000
	s_mov_b32 s47, 0xa000
	s_mov_b32 s48, 0xc000
	s_mov_b32 s49, 0xe000
	s_mov_b32 s50, 0x10000
	s_mov_b32 s51, 0x12000
	v_lshlrev_b32_e32 v4, 2, v4
	s_mov_b64 s[12:13], 0x1400
	s_movk_i32 s52, 0x1000
	s_mov_b32 s53, s2
	s_ashr_i32 s55, s53, 7
	s_bfe_u32 s54, s53, 0x20005
	s_mul_i32 s56, s55, 0x900000
	s_mul_hi_i32 s10, s55, 0x900000
	s_add_u32 s58, s22, s56
	s_addc_u32 s59, s23, s10
	s_lshl_b32 s10, s53, 5
	s_and_b32 s56, s10, 0x3e0
	v_add_u32_e32 v10, s56, v1
	v_mov_b64_e32 v[8:9], s[58:59]
	v_mad_i64_i32 v[8:9], s[58:59], v10, s37, v[8:9]
	s_lshl_b32 s10, s54, 9
	v_lshl_add_u64 v[8:9], v[8:9], 0, s[10:11]
	s_lshl_b32 s10, s55, 2
	s_or_b32 s58, s10, s54
	v_lshl_add_u64 v[8:9], v[8:9], 0, v[4:5]
	s_ashr_i32 s59, s58, 31
	v_add_co_u32_e32 v10, vcc, s52, v8
	s_lshl_b64 s[58:59], s[58:59], 17
	s_nop 0
	v_addc_co_u32_e32 v11, vcc, 0, v9, vcc
	v_lshl_add_u64 v[86:87], v[6:7], 0, s[58:59]
	v_add_co_u32_e32 v20, vcc, s44, v86
	v_lshl_add_u64 v[12:13], v[8:9], 0, s[12:13]
	s_nop 0
	v_addc_co_u32_e32 v21, vcc, 0, v87, vcc
	v_add_co_u32_e32 v38, vcc, s3, v86
	s_waitcnt lgkmcnt(0)
	s_nop 0
	v_addc_co_u32_e32 v39, vcc, 0, v87, vcc
	v_add_co_u32_e32 v42, vcc, s45, v86
	s_barrier
	s_nop 0
	v_addc_co_u32_e32 v43, vcc, 0, v87, vcc
	v_add_co_u32_e32 v46, vcc, s46, v86
	s_nop 1
	v_addc_co_u32_e32 v47, vcc, 0, v87, vcc
	v_add_co_u32_e32 v50, vcc, s47, v86
	global_load_dwordx4 v[8:11], v[10:11], off offset:1024
	s_nop 0
	global_load_dwordx4 v[12:15], v[12:13], off offset:16
	v_addc_co_u32_e32 v51, vcc, 0, v87, vcc
	v_add_co_u32_e32 v54, vcc, s48, v86
	global_load_dwordx4 v[16:19], v[86:87], off
	s_nop 0
	global_load_dwordx4 v[20:23], v[20:21], off
	v_addc_co_u32_e32 v55, vcc, 0, v87, vcc
	v_add_co_u32_e32 v58, vcc, s49, v86
	global_load_dwordx4 v[38:41], v[38:39], off
	s_nop 0
	global_load_dwordx4 v[42:45], v[42:43], off
	v_addc_co_u32_e32 v59, vcc, 0, v87, vcc
	v_add_co_u32_e32 v62, vcc, s50, v86
	global_load_dwordx4 v[46:49], v[46:47], off
	s_nop 0
	global_load_dwordx4 v[50:53], v[50:51], off
	v_addc_co_u32_e32 v63, vcc, 0, v87, vcc
	v_add_co_u32_e32 v66, vcc, s51, v86
	s_mov_b32 s10, -4
	s_nop 0
	v_addc_co_u32_e32 v67, vcc, 0, v87, vcc
	v_add_co_u32_e32 v70, vcc, s14, v86
	v_mov_b32_e32 v37, v26
	s_nop 0
	v_addc_co_u32_e32 v71, vcc, 0, v87, vcc
	v_add_co_u32_e32 v74, vcc, s15, v86
	s_nop 1
	v_addc_co_u32_e32 v75, vcc, 0, v87, vcc
	v_add_co_u32_e32 v78, vcc, s33, v86
	global_load_dwordx4 v[54:57], v[54:55], off
	s_nop 0
	global_load_dwordx4 v[58:61], v[58:59], off
	s_nop 0
	global_load_dwordx4 v[62:65], v[62:63], off
	s_nop 0
	global_load_dwordx4 v[66:69], v[66:67], off
	s_nop 0
	global_load_dwordx4 v[70:73], v[70:71], off
	s_nop 0
	global_load_dwordx4 v[74:77], v[74:75], off
	v_addc_co_u32_e32 v79, vcc, 0, v87, vcc
	v_add_co_u32_e32 v82, vcc, s34, v86
	s_nop 1
	v_addc_co_u32_e32 v83, vcc, 0, v87, vcc
	v_add_co_u32_e32 v88, vcc, s35, v86
	global_load_dwordx4 v[78:81], v[78:79], off
	s_nop 0
	global_load_dwordx4 v[82:85], v[82:83], off
	v_addc_co_u32_e32 v89, vcc, 0, v87, vcc
	v_add_co_u32_e32 v90, vcc, s36, v86
	s_nop 1
	v_addc_co_u32_e32 v91, vcc, 0, v87, vcc
	global_load_dwordx4 v[86:89], v[88:89], off
	s_nop 0
	global_load_dwordx4 v[90:93], v[90:91], off
	v_add_u32_e32 v108, 0x100, v0
	v_lshlrev_b32_e32 v110, 4, v108
	s_load_dword s9, s[0:1], 0x60
	s_add_u32 s6, s40, 0x1fb00000
	v_lshlrev_b32_e32 v101, 1, v108
	v_and_b32_e32 v102, 0x90, v110
	s_movk_i32 s3, 0x6c
	v_lshlrev_b32_e32 v103, 3, v108
	v_ashrrev_i32_e32 v109, 31, v108
	s_addc_u32 s7, s41, 0
	v_and_or_b32 v102, v101, s3, v102
	v_ashrrev_i32_e32 v111, 6, v108
	v_ashrrev_i32_e32 v101, 4, v108
	v_and_b32_e32 v104, 0x78, v103
	v_lshl_add_u64 v[106:107], v[108:109], 4, s[40:41]
	s_mov_b64 s[4:5], 0x20a00000
	v_and_b32_e32 v108, 63, v108
	v_lshl_add_u64 v[106:107], v[106:107], 0, s[4:5]
	v_lshlrev_b32_e32 v103, 9, v101
	v_lshlrev_b32_e32 v109, 2, v104
	v_add_u32_e32 v124, 0, v110
	s_add_u32 s4, s0, 0x60
	v_lshl_add_u32 v108, v108, 4, 0
	v_mov_b32_e32 v105, 0
	s_mov_b32 s11, 0
	v_add3_u32 v103, 0, v103, v109
	s_movk_i32 s3, 0x4000
	v_add_u32_e32 v125, 0x4000, v124
	v_lshl_add_u32 v126, v111, 11, 0
; #define LAS __attribute__((address_space(3)))
; __device__ void p_weights_prod(const Args& a, LAS unsigned char* lds) {
;     ...
;         {
;             const int rr = tid >> 4, c8 = (tid & 15) * 8;
;             const float* src = a.w_in + (size_t)l * DM * INW + (size_t)(kblk * 32 + rr) * INW + 1280 + g * 128 + c8;
;             const f32x4* msrc = (const f32x4*)(MM + (size_t)(l * 4 + g) * 128 * 256) + tid;
;             f32x4 mreg[16];
; #pragma unroll
;             for (int j = 0; j < 16; ++j) mreg[j] = msrc[j * NTHREADS];
;             *(LAS f32x4*)(wt + rr * 128 + c8) = *(const f32x4*)src; *(LAS f32x4*)(wt + rr * 128 + c8 + 4) = *(const f32x4*)(src + 4);
; #pragma unroll
;             for (int j = 0; j < 16; ++j) ((LAS f32x4*)mmt)[tid + j * NTHREADS] = mreg[j];
;         }
;         __syncthreads();
;         f32x4 acc[4];
; #pragma unroll
;         for (int r2 = 0; r2 < 4; ++r2) acc[r2] = (f32x4){0.f, 0.f, 0.f, 0.f};
	v_lshlrev_b32_e32 v127, 2, v111
	s_addc_u32 s5, s1, 0
	s_mov_b32 s14, 0x14000
	v_add_u32_e32 v128, 0x14000, v124
	s_mov_b32 s15, 0x16000
	v_add_u32_e32 v129, 0x16000, v124
	s_mov_b32 s33, 0x18000
	v_add_u32_e32 v130, 0x18000, v124
	s_mov_b32 s34, 0x1a000
	v_add_u32_e32 v131, 0x1a000, v124
	s_mov_b32 s35, 0x1c000
	v_add_u32_e32 v132, 0x1c000, v124
	s_mov_b32 s36, 0x1e000
	v_add_u32_e32 v133, 0x1e000, v124
	v_add_u32_e32 v134, 0x20000, v124
	v_add_u32_e32 v135, 0x22000, v124
	v_add_u32_e32 v136, 0x4000, v108
	s_movk_i32 s37, 0x2400
	s_movk_i32 s44, 0x2000
	s_movk_i32 s45, 0x6000
	s_mov_b32 s46, 0x8000
	s_mov_b32 s47, 0xa000
	s_mov_b32 s48, 0xc000
	s_mov_b32 s49, 0xe000
	s_mov_b32 s50, 0x10000
	s_mov_b32 s51, 0x12000
	v_lshlrev_b32_e32 v104, 2, v104
	s_mov_b64 s[12:13], 0x1400
	s_movk_i32 s52, 0x1000
	s_mov_b32 s53, s2
	s_ashr_i32 s55, s53, 7
	s_bfe_u32 s54, s53, 0x20005
	s_mul_i32 s56, s55, 0x900000
	s_mul_hi_i32 s10, s55, 0x900000
	s_add_u32 s58, s22, s56
	s_addc_u32 s59, s23, s10
	s_lshl_b32 s10, s53, 5
	s_and_b32 s56, s10, 0x3e0
	v_add_u32_e32 v110, s56, v101
	v_mov_b64_e32 v[108:109], s[58:59]
	v_mad_i64_i32 v[108:109], s[58:59], v110, s37, v[108:109]
	s_lshl_b32 s10, s54, 9
	v_lshl_add_u64 v[108:109], v[108:109], 0, s[10:11]
	s_lshl_b32 s10, s55, 2
	s_or_b32 s58, s10, s54
	v_lshl_add_u64 v[108:109], v[108:109], 0, v[104:105]
	s_ashr_i32 s59, s58, 31
	v_add_co_u32_e32 v110, vcc, s52, v108
	s_lshl_b64 s[58:59], s[58:59], 17
	s_nop 0
	v_addc_co_u32_e32 v111, vcc, 0, v109, vcc
	v_lshl_add_u64 v[186:187], v[106:107], 0, s[58:59]
	v_add_co_u32_e32 v120, vcc, s44, v186
	v_lshl_add_u64 v[112:113], v[108:109], 0, s[12:13]
	s_nop 0
	v_addc_co_u32_e32 v121, vcc, 0, v187, vcc
	v_add_co_u32_e32 v138, vcc, s3, v186
	s_waitcnt lgkmcnt(0)
	s_nop 0
	v_addc_co_u32_e32 v139, vcc, 0, v187, vcc
	v_add_co_u32_e32 v142, vcc, s45, v186
	s_nop 0
	v_addc_co_u32_e32 v143, vcc, 0, v187, vcc
	v_add_co_u32_e32 v146, vcc, s46, v186
	s_nop 1
	v_addc_co_u32_e32 v147, vcc, 0, v187, vcc
	v_add_co_u32_e32 v150, vcc, s47, v186
	global_load_dwordx4 v[108:111], v[110:111], off offset:1024
	s_nop 0
	global_load_dwordx4 v[112:115], v[112:113], off offset:16
	v_addc_co_u32_e32 v151, vcc, 0, v187, vcc
	v_add_co_u32_e32 v154, vcc, s48, v186
	global_load_dwordx4 v[116:119], v[186:187], off
	s_nop 0
	global_load_dwordx4 v[120:123], v[120:121], off
	v_addc_co_u32_e32 v155, vcc, 0, v187, vcc
	v_add_co_u32_e32 v158, vcc, s49, v186
	global_load_dwordx4 v[138:141], v[138:139], off
	s_nop 0
	global_load_dwordx4 v[142:145], v[142:143], off
	v_addc_co_u32_e32 v159, vcc, 0, v187, vcc
	v_add_co_u32_e32 v162, vcc, s50, v186
	global_load_dwordx4 v[146:149], v[146:147], off
	s_nop 0
	global_load_dwordx4 v[150:153], v[150:151], off
	v_addc_co_u32_e32 v163, vcc, 0, v187, vcc
	v_add_co_u32_e32 v166, vcc, s51, v186
	s_mov_b32 s10, -4
	s_nop 0
	v_addc_co_u32_e32 v167, vcc, 0, v187, vcc
	v_add_co_u32_e32 v170, vcc, s14, v186
	v_mov_b32_e32 v137, v126
	s_nop 0
	v_addc_co_u32_e32 v171, vcc, 0, v187, vcc
	v_add_co_u32_e32 v174, vcc, s15, v186
	s_nop 1
	v_addc_co_u32_e32 v175, vcc, 0, v187, vcc
	v_add_co_u32_e32 v178, vcc, s33, v186
	global_load_dwordx4 v[154:157], v[154:155], off
	s_nop 0
	global_load_dwordx4 v[158:161], v[158:159], off
	s_nop 0
	global_load_dwordx4 v[162:165], v[162:163], off
	s_nop 0
	global_load_dwordx4 v[166:169], v[166:167], off
	s_nop 0
	global_load_dwordx4 v[170:173], v[170:171], off
	s_nop 0
	global_load_dwordx4 v[174:177], v[174:175], off
	v_addc_co_u32_e32 v179, vcc, 0, v187, vcc
	v_add_co_u32_e32 v182, vcc, s34, v186
	s_nop 1
	v_addc_co_u32_e32 v183, vcc, 0, v187, vcc
	v_add_co_u32_e32 v188, vcc, s35, v186
	global_load_dwordx4 v[178:181], v[178:179], off
	s_nop 0
	global_load_dwordx4 v[182:185], v[182:183], off
	v_addc_co_u32_e32 v189, vcc, 0, v187, vcc
	v_add_co_u32_e32 v190, vcc, s36, v186
	s_nop 1
	v_addc_co_u32_e32 v191, vcc, 0, v187, vcc
	global_load_dwordx4 v[186:189], v[188:189], off
	s_nop 0
	global_load_dwordx4 v[190:193], v[190:191], off
	s_waitcnt vmcnt(0)
	ds_write_b128 v3, v[8:11]
	ds_write_b128 v3, v[12:15] offset:16
	ds_write_b128 v24, v[16:19] offset:16384
	ds_write_b128 v24, v[20:23] offset:24576
	ds_write_b128 v24, v[38:41] offset:32768
	ds_write_b128 v24, v[42:45] offset:40960
	ds_write_b128 v24, v[46:49] offset:49152
	ds_write_b128 v24, v[50:53] offset:57344
	ds_write_b128 v25, v[54:57] offset:49152
	ds_write_b128 v25, v[58:61] offset:57344
	ds_write_b128 v28, v[62:65]
	ds_write_b128 v29, v[66:69]
	ds_write_b128 v30, v[70:73]
	ds_write_b128 v31, v[74:77]
	ds_write_b128 v32, v[78:81]
	ds_write_b128 v33, v[82:85]
	ds_write_b128 v34, v[86:89]
	ds_write_b128 v35, v[90:93]
	v_mov_b32_e32 v38, v36
	v_mov_b32_e32 v10, 0
	v_mov_b32_e32 v11, v5
	v_mov_b32_e32 v8, 0
	v_mov_b32_e32 v9, v5
	v_mov_b32_e32 v22, 0
	v_mov_b32_e32 v23, v5
	v_mov_b32_e32 v20, 0
	v_mov_b32_e32 v21, v5
	v_mov_b32_e32 v14, 0
	v_mov_b32_e32 v15, v5
	v_mov_b32_e32 v12, 0
	v_mov_b32_e32 v13, v5
	v_mov_b32_e32 v18, 0
	v_mov_b32_e32 v19, v5
	v_mov_b32_e32 v16, 0
	v_mov_b32_e32 v17, v5
	s_waitcnt vmcnt(0)
	ds_write_b128 v103, v[108:111]
	ds_write_b128 v103, v[112:115] offset:16
	ds_write_b128 v124, v[116:119] offset:16384
	ds_write_b128 v124, v[120:123] offset:24576
	ds_write_b128 v124, v[138:141] offset:32768
	ds_write_b128 v124, v[142:145] offset:40960
	ds_write_b128 v124, v[146:149] offset:49152
	ds_write_b128 v124, v[150:153] offset:57344
	ds_write_b128 v125, v[154:157] offset:49152
	ds_write_b128 v125, v[158:161] offset:57344
	ds_write_b128 v128, v[162:165]
	ds_write_b128 v129, v[166:169]
	ds_write_b128 v130, v[170:173]
	ds_write_b128 v131, v[174:177]
	ds_write_b128 v132, v[178:181]
	ds_write_b128 v133, v[182:185]
	ds_write_b128 v134, v[186:189]
	ds_write_b128 v135, v[190:193]
	v_mov_b32_e32 v138, v136
	v_mov_b32_e32 v110, 0
	v_mov_b32_e32 v111, v105
	v_mov_b32_e32 v108, 0
	v_mov_b32_e32 v109, v105
	v_mov_b32_e32 v122, 0
	v_mov_b32_e32 v123, v105
	v_mov_b32_e32 v120, 0
	v_mov_b32_e32 v121, v105
	v_mov_b32_e32 v114, 0
	v_mov_b32_e32 v115, v105
	v_mov_b32_e32 v112, 0
	v_mov_b32_e32 v113, v105
	v_mov_b32_e32 v118, 0
	v_mov_b32_e32 v119, v105
	v_mov_b32_e32 v116, 0
	v_mov_b32_e32 v117, v105
	s_waitcnt lgkmcnt(0)
	s_barrier
; #define LAS __attribute__((address_space(3)))
; __device__ void p_weights_prod(const Args& a, LAS unsigned char* lds) {
;     ...
;         f32x4 acc[4];
; #pragma unroll
;         for (int r2 = 0; r2 < 4; ++r2) acc[r2] = (f32x4){0.f, 0.f, 0.f, 0.f};
; #pragma unroll 2
;         for (int c0 = 0; c0 < 128; c0 += 4) {
;             f32x4 w4[4], m4[4];
; #pragma unroll
;             for (int r2 = 0; r2 < 4; ++r2) w4[r2] = *(const LAS f32x4*)(wt + (4 * rq + r2) * 128 + c0);
; #pragma unroll
;             for (int cc = 0; cc < 4; ++cc) m4[cc] = *(const LAS f32x4*)(mmt + (c0 + cc) * 256 + lc0);
; #pragma unroll
;             for (int r2 = 0; r2 < 4; ++r2)
; #pragma unroll
;                 for (int cc = 0; cc < 4; ++cc) acc[r2] += m4[cc] * w4[r2][cc];
;         }
;         const int k0 = kblk * 32 + 4 * rq;
;         const f32x4 gn = *(const f32x4*)(a.norm_gain + l * DM + k0);
	v_mov_b32_e32 v8, v0
	v_lshlrev_b32_e32 v10, 4, v8
	s_load_dword s9, s[0:1], 0x60
	s_add_u32 s6, s40, 0x1fb00000
	v_lshlrev_b32_e32 v1, 1, v8
	v_and_b32_e32 v2, 0x90, v10
	s_movk_i32 s3, 0x6c
	v_lshlrev_b32_e32 v3, 3, v8
	v_ashrrev_i32_e32 v9, 31, v8
	s_addc_u32 s7, s41, 0
	v_and_or_b32 v2, v1, s3, v2
	v_ashrrev_i32_e32 v11, 6, v8
	v_ashrrev_i32_e32 v1, 4, v8
	v_and_b32_e32 v4, 0x78, v3
	v_lshl_add_u64 v[6:7], v[8:9], 4, s[40:41]
	s_mov_b64 s[4:5], 0x20a00000
	v_and_b32_e32 v8, 63, v8
	v_lshl_add_u64 v[6:7], v[6:7], 0, s[4:5]
	v_lshlrev_b32_e32 v3, 9, v1
	v_lshlrev_b32_e32 v9, 2, v4
	v_add_u32_e32 v24, 0, v10
	s_add_u32 s4, s0, 0x60
	v_lshl_add_u32 v8, v8, 4, 0
	v_mov_b32_e32 v5, 0
	s_mov_b32 s11, 0
	v_add3_u32 v3, 0, v3, v9
	s_movk_i32 s3, 0x4000
	v_add_u32_e32 v25, 0x4000, v24
	v_lshl_add_u32 v26, v11, 11, 0
	v_lshlrev_b32_e32 v27, 2, v11
	s_addc_u32 s5, s1, 0
	s_mov_b32 s14, 0x14000
	v_add_u32_e32 v28, 0x14000, v24
	s_mov_b32 s15, 0x16000
	v_add_u32_e32 v29, 0x16000, v24
	s_mov_b32 s33, 0x18000
	v_add_u32_e32 v30, 0x18000, v24
	s_mov_b32 s34, 0x1a000
	v_add_u32_e32 v31, 0x1a000, v24
	s_mov_b32 s35, 0x1c000
	v_add_u32_e32 v32, 0x1c000, v24
	s_mov_b32 s36, 0x1e000
	v_add_u32_e32 v33, 0x1e000, v24
	v_add_u32_e32 v34, 0x20000, v24
	v_add_u32_e32 v35, 0x22000, v24
	v_add_u32_e32 v36, 0x4000, v8
	s_movk_i32 s37, 0x2400
	s_movk_i32 s44, 0x2000
	s_movk_i32 s45, 0x6000
	s_mov_b32 s46, 0x8000
	s_mov_b32 s47, 0xa000
	s_mov_b32 s48, 0xc000
	s_mov_b32 s49, 0xe000
	s_mov_b32 s50, 0x10000
	s_mov_b32 s51, 0x12000
	v_lshlrev_b32_e32 v4, 2, v4
	s_mov_b64 s[12:13], 0x1400
	s_movk_i32 s52, 0x1000
	s_mov_b32 s53, s2
	s_ashr_i32 s55, s53, 7
	s_bfe_u32 s54, s53, 0x20005
	s_mul_i32 s56, s55, 0x900000
	s_mul_hi_i32 s10, s55, 0x900000
	s_add_u32 s58, s22, s56
	s_addc_u32 s59, s23, s10
	s_lshl_b32 s10, s53, 5
	s_and_b32 s56, s10, 0x3e0
	v_add_u32_e32 v10, s56, v1
	v_mov_b64_e32 v[8:9], s[58:59]
	v_mad_i64_i32 v[8:9], s[58:59], v10, s37, v[8:9]
	s_lshl_b32 s10, s54, 9
	v_lshl_add_u64 v[8:9], v[8:9], 0, s[10:11]
	s_lshl_b32 s10, s55, 2
	s_or_b32 s58, s10, s54
	v_lshl_add_u64 v[8:9], v[8:9], 0, v[4:5]
	s_ashr_i32 s59, s58, 31
	v_add_co_u32_e32 v10, vcc, s52, v8
	s_lshl_b64 s[58:59], s[58:59], 17
	s_nop 0
	v_addc_co_u32_e32 v11, vcc, 0, v9, vcc
	v_lshl_add_u64 v[86:87], v[6:7], 0, s[58:59]
	v_add_co_u32_e32 v20, vcc, s44, v86
	v_lshl_add_u64 v[12:13], v[8:9], 0, s[12:13]
	s_nop 0
	v_addc_co_u32_e32 v21, vcc, 0, v87, vcc
	v_add_co_u32_e32 v38, vcc, s3, v86
	s_waitcnt lgkmcnt(0)
	s_nop 0
	v_addc_co_u32_e32 v39, vcc, 0, v87, vcc
	v_add_co_u32_e32 v42, vcc, s45, v86
	s_nop 0
	v_addc_co_u32_e32 v43, vcc, 0, v87, vcc
	v_add_co_u32_e32 v46, vcc, s46, v86
	s_nop 1
	v_addc_co_u32_e32 v47, vcc, 0, v87, vcc
	v_add_co_u32_e32 v50, vcc, s47, v86
	s_nop 0
	v_addc_co_u32_e32 v51, vcc, 0, v87, vcc
	v_add_co_u32_e32 v54, vcc, s48, v86
	s_nop 0
	v_addc_co_u32_e32 v55, vcc, 0, v87, vcc
	v_add_co_u32_e32 v58, vcc, s49, v86
	s_nop 0
	v_addc_co_u32_e32 v59, vcc, 0, v87, vcc
	v_add_co_u32_e32 v62, vcc, s50, v86
	s_nop 0
	v_addc_co_u32_e32 v63, vcc, 0, v87, vcc
	v_add_co_u32_e32 v66, vcc, s51, v86
	s_mov_b32 s10, -4
	s_nop 0
	v_addc_co_u32_e32 v67, vcc, 0, v87, vcc
	v_add_co_u32_e32 v70, vcc, s14, v86
	v_mov_b32_e32 v37, v26
	s_nop 0
	v_addc_co_u32_e32 v71, vcc, 0, v87, vcc
	v_add_co_u32_e32 v74, vcc, s15, v86
	s_nop 1
	v_addc_co_u32_e32 v75, vcc, 0, v87, vcc
	v_add_co_u32_e32 v78, vcc, s33, v86
	s_nop 0
	s_nop 0
	s_nop 0
	s_nop 0
	s_nop 0
	v_addc_co_u32_e32 v79, vcc, 0, v87, vcc
	v_add_co_u32_e32 v82, vcc, s34, v86
	s_nop 1
	v_addc_co_u32_e32 v83, vcc, 0, v87, vcc
	v_add_co_u32_e32 v88, vcc, s35, v86
	s_nop 0
	v_addc_co_u32_e32 v89, vcc, 0, v87, vcc
	v_add_co_u32_e32 v90, vcc, s36, v86
	s_nop 1
	v_addc_co_u32_e32 v91, vcc, 0, v87, vcc
	s_nop 0
	s_waitcnt vmcnt(0)
	v_mov_b32_e32 v38, v36
	v_mov_b32_e32 v10, 0
	v_mov_b32_e32 v11, v5
	v_mov_b32_e32 v8, 0
	v_mov_b32_e32 v9, v5
	v_mov_b32_e32 v22, 0
	v_mov_b32_e32 v23, v5
	v_mov_b32_e32 v20, 0
	v_mov_b32_e32 v21, v5
	v_mov_b32_e32 v14, 0
	v_mov_b32_e32 v15, v5
	v_mov_b32_e32 v12, 0
	v_mov_b32_e32 v13, v5
	v_mov_b32_e32 v18, 0
	v_mov_b32_e32 v19, v5
	v_mov_b32_e32 v16, 0
	v_mov_b32_e32 v17, v5
	v_add_u32_e32 v124, s56, v27
	s_lshl_b32 s58, s55, 10
	s_ashr_i32 s59, s58, 31
	s_lshl_b64 s[58:59], s[58:59], 2
	s_add_u32 s58, s20, s58
	s_addc_u32 s59, s21, s59
	v_ashrrev_i32_e32 v125, 31, v124
	v_lshl_add_u64 v[126:127], v[124:125], 2, s[58:59]
	global_load_dwordx4 v[120:123], v[126:127], off
; #define LAS __attribute__((address_space(3)))
; __device__ void p_weights_prod(const Args& a, LAS unsigned char* lds) {
;     ...
; #pragma unroll 2
;         for (int c0 = 0; c0 < 128; c0 += 4) {
;             f32x4 w4[4], m4[4];
; #pragma unroll
;             for (int r2 = 0; r2 < 4; ++r2) w4[r2] = *(const LAS f32x4*)(wt + (4 * rq + r2) * 128 + c0);
; #pragma unroll
;             for (int cc = 0; cc < 4; ++cc) m4[cc] = *(const LAS f32x4*)(mmt + (c0 + cc) * 256 + lc0);
; #pragma unroll
;             for (int r2 = 0; r2 < 4; ++r2)
; #pragma unroll
;                 for (int cc = 0; cc < 4; ++cc) acc[r2] += m4[cc] * w4[r2][cc];
;         }
.Lpw_ka:
	ds_read_b128 v[40:43], v38
	ds_read_b128 v[44:47], v38 offset:1024
	ds_read_b128 v[48:51], v38 offset:2048
	ds_read_b128 v[52:55], v38 offset:3072
	ds_read_b128 v[56:59], v37
	ds_read_b128 v[60:63], v37 offset:16
	ds_read_b128 v[64:67], v37 offset:512
	ds_read_b128 v[68:71], v37 offset:528
	ds_read_b128 v[72:75], v37 offset:1024
	ds_read_b128 v[76:79], v37 offset:1040
	ds_read_b128 v[80:83], v37 offset:1536
	ds_read_b128 v[84:87], v37 offset:1552
	ds_read_b128 v[88:91], v38 offset:4096
	ds_read_b128 v[92:95], v38 offset:5120
	ds_read_b128 v[96:99], v38 offset:6144
	ds_read_b128 v[100:103], v38 offset:7168
	s_waitcnt lgkmcnt(11)
	v_pk_fma_f32 v[8:9], v[56:57], v[42:43], v[8:9] op_sel_hi:[0,1,1]
	v_pk_fma_f32 v[10:11], v[56:57], v[40:41], v[10:11] op_sel_hi:[0,1,1]
	s_waitcnt lgkmcnt(9)
	v_pk_fma_f32 v[20:21], v[64:65], v[42:43], v[20:21] op_sel_hi:[0,1,1]
	v_pk_fma_f32 v[22:23], v[64:65], v[40:41], v[22:23] op_sel_hi:[0,1,1]
	s_waitcnt lgkmcnt(7)
	v_pk_fma_f32 v[12:13], v[72:73], v[42:43], v[12:13] op_sel_hi:[0,1,1]
	v_pk_fma_f32 v[14:15], v[72:73], v[40:41], v[14:15] op_sel_hi:[0,1,1]
	s_waitcnt lgkmcnt(5)
	v_pk_fma_f32 v[16:17], v[42:43], v[80:81], v[16:17] op_sel_hi:[1,0,1]
	v_pk_fma_f32 v[18:19], v[40:41], v[80:81], v[18:19] op_sel_hi:[1,0,1]
	v_pk_fma_f32 v[8:9], v[56:57], v[46:47], v[8:9] op_sel:[1,0,0]
	v_pk_fma_f32 v[10:11], v[56:57], v[44:45], v[10:11] op_sel:[1,0,0]
	v_pk_fma_f32 v[20:21], v[64:65], v[46:47], v[20:21] op_sel:[1,0,0]
	v_pk_fma_f32 v[22:23], v[64:65], v[44:45], v[22:23] op_sel:[1,0,0]
	v_pk_fma_f32 v[12:13], v[72:73], v[46:47], v[12:13] op_sel:[1,0,0]
	v_pk_fma_f32 v[14:15], v[72:73], v[44:45], v[14:15] op_sel:[1,0,0]
	v_pk_fma_f32 v[16:17], v[80:81], v[46:47], v[16:17] op_sel:[1,0,0]
	v_pk_fma_f32 v[18:19], v[80:81], v[44:45], v[18:19] op_sel:[1,0,0]
	v_mov_b32_e32 v40, v59
	v_mov_b32_e32 v42, v67
	v_mov_b32_e32 v104, v75
	v_mov_b32_e32 v106, v83
	v_pk_fma_f32 v[10:11], v[58:59], v[48:49], v[10:11] op_sel_hi:[0,1,1]
	v_pk_fma_f32 v[8:9], v[58:59], v[50:51], v[8:9] op_sel_hi:[0,1,1]
	v_pk_fma_f32 v[22:23], v[66:67], v[48:49], v[22:23] op_sel_hi:[0,1,1]
	v_pk_fma_f32 v[20:21], v[66:67], v[50:51], v[20:21] op_sel_hi:[0,1,1]
	v_pk_fma_f32 v[14:15], v[74:75], v[48:49], v[14:15] op_sel_hi:[0,1,1]
	v_pk_fma_f32 v[12:13], v[74:75], v[50:51], v[12:13] op_sel_hi:[0,1,1]
	v_pk_fma_f32 v[18:19], v[82:83], v[48:49], v[18:19] op_sel_hi:[0,1,1]
	v_pk_fma_f32 v[16:17], v[82:83], v[50:51], v[16:17] op_sel_hi:[0,1,1]
	v_pk_fma_f32 v[8:9], v[40:41], v[54:55], v[8:9] op_sel_hi:[0,1,1]
	v_pk_fma_f32 v[10:11], v[40:41], v[52:53], v[10:11] op_sel_hi:[0,1,1]
	v_pk_fma_f32 v[20:21], v[42:43], v[54:55], v[20:21] op_sel_hi:[0,1,1]
	v_pk_fma_f32 v[22:23], v[42:43], v[52:53], v[22:23] op_sel_hi:[0,1,1]
	v_pk_fma_f32 v[12:13], v[104:105], v[54:55], v[12:13] op_sel_hi:[0,1,1]
	v_pk_fma_f32 v[14:15], v[104:105], v[52:53], v[14:15] op_sel_hi:[0,1,1]
	v_pk_fma_f32 v[16:17], v[106:107], v[54:55], v[16:17] op_sel_hi:[0,1,1]
	v_pk_fma_f32 v[18:19], v[106:107], v[52:53], v[18:19] op_sel_hi:[0,1,1]
	s_waitcnt lgkmcnt(3)
	v_pk_fma_f32 v[10:11], v[60:61], v[88:89], v[10:11] op_sel_hi:[0,1,1]
	v_pk_fma_f32 v[8:9], v[60:61], v[90:91], v[8:9] op_sel_hi:[0,1,1]
	v_pk_fma_f32 v[22:23], v[68:69], v[88:89], v[22:23] op_sel_hi:[0,1,1]
	v_pk_fma_f32 v[20:21], v[68:69], v[90:91], v[20:21] op_sel_hi:[0,1,1]
	v_pk_fma_f32 v[14:15], v[76:77], v[88:89], v[14:15] op_sel_hi:[0,1,1]
	v_pk_fma_f32 v[12:13], v[76:77], v[90:91], v[12:13] op_sel_hi:[0,1,1]
	v_pk_fma_f32 v[18:19], v[88:89], v[84:85], v[18:19] op_sel_hi:[1,0,1]
	v_pk_fma_f32 v[16:17], v[90:91], v[84:85], v[16:17] op_sel_hi:[1,0,1]
	s_waitcnt lgkmcnt(2)
	v_pk_fma_f32 v[8:9], v[60:61], v[94:95], v[8:9] op_sel:[1,0,0]
	v_pk_fma_f32 v[10:11], v[60:61], v[92:93], v[10:11] op_sel:[1,0,0]
	v_pk_fma_f32 v[20:21], v[68:69], v[94:95], v[20:21] op_sel:[1,0,0]
	v_pk_fma_f32 v[22:23], v[68:69], v[92:93], v[22:23] op_sel:[1,0,0]
	v_pk_fma_f32 v[12:13], v[76:77], v[94:95], v[12:13] op_sel:[1,0,0]
	v_pk_fma_f32 v[14:15], v[76:77], v[92:93], v[14:15] op_sel:[1,0,0]
	v_pk_fma_f32 v[16:17], v[84:85], v[94:95], v[16:17] op_sel:[1,0,0]
	v_pk_fma_f32 v[18:19], v[84:85], v[92:93], v[18:19] op_sel:[1,0,0]
	s_add_i32 s10, s10, 8
	v_mov_b32_e32 v108, v63
	v_mov_b32_e32 v110, v71
	v_mov_b32_e32 v112, v79
	v_mov_b32_e32 v114, v87
	s_waitcnt lgkmcnt(1)
	v_pk_fma_f32 v[10:11], v[62:63], v[96:97], v[10:11] op_sel_hi:[0,1,1]
	v_pk_fma_f32 v[8:9], v[62:63], v[98:99], v[8:9] op_sel_hi:[0,1,1]
	v_pk_fma_f32 v[22:23], v[70:71], v[96:97], v[22:23] op_sel_hi:[0,1,1]
	v_pk_fma_f32 v[20:21], v[70:71], v[98:99], v[20:21] op_sel_hi:[0,1,1]
	v_pk_fma_f32 v[14:15], v[78:79], v[96:97], v[14:15] op_sel_hi:[0,1,1]
	v_pk_fma_f32 v[12:13], v[78:79], v[98:99], v[12:13] op_sel_hi:[0,1,1]
	v_pk_fma_f32 v[18:19], v[86:87], v[96:97], v[18:19] op_sel_hi:[0,1,1]
	v_pk_fma_f32 v[16:17], v[86:87], v[98:99], v[16:17] op_sel_hi:[0,1,1]
	v_add_u32_e32 v38, 0x2000, v38
	v_add_u32_e32 v37, 32, v37
	s_cmpk_gt_u32 s10, 0x7b
	s_waitcnt lgkmcnt(0)
	v_pk_fma_f32 v[8:9], v[108:109], v[102:103], v[8:9] op_sel_hi:[0,1,1]
	v_pk_fma_f32 v[10:11], v[108:109], v[100:101], v[10:11] op_sel_hi:[0,1,1]
	v_pk_fma_f32 v[20:21], v[110:111], v[102:103], v[20:21] op_sel_hi:[0,1,1]
	v_pk_fma_f32 v[22:23], v[110:111], v[100:101], v[22:23] op_sel_hi:[0,1,1]
	v_pk_fma_f32 v[12:13], v[112:113], v[102:103], v[12:13] op_sel_hi:[0,1,1]
	v_pk_fma_f32 v[14:15], v[112:113], v[100:101], v[14:15] op_sel_hi:[0,1,1]
	v_pk_fma_f32 v[16:17], v[114:115], v[102:103], v[16:17] op_sel_hi:[0,1,1]
	v_pk_fma_f32 v[18:19], v[114:115], v[100:101], v[18:19] op_sel_hi:[0,1,1]
	s_cbranch_scc0 .Lpw_ka
; __device__ void p_weights_prod(const Args& a, LAS unsigned char* lds) {
;     ...
;         const int k0 = kblk * 32 + 4 * rq;
;         const f32x4 gn = *(const f32x4*)(a.norm_gain + l * DM + k0);
; #pragma unroll
;         for (int j = 0; j < 4; ++j) {
;             f16x4 o;
; #pragma unroll
;             for (int r2 = 0; r2 < 4; ++r2) o[r2] = (f16)(acc[r2][j] * gn[r2]);
;             *(f16x4*)(W1T + ((size_t)l * N1 + pn * 256 + rho0 + j) * 1024 + k0) = o;
;         }
	v_add_u32_e32 v42, s56, v27
	s_lshl_b32 s56, s55, 10
	s_ashr_i32 s57, s56, 31
	s_lshl_b64 s[56:57], s[56:57], 2
	s_add_u32 s56, s20, s56
	s_addc_u32 s57, s21, s57
	v_ashrrev_i32_e32 v43, 31, v42
	s_lshl_b32 s54, s54, 8
	s_mul_hi_i32 s10, s55, 0xb00
	s_mulk_i32 s55, 0xb00
	s_addk_i32 s54, 0x700
	s_add_u32 s54, s55, s54
	s_addc_u32 s10, s10, 0
	v_mov_b32_e32 v44, v22
	v_mov_b32_e32 v45, v14
	v_mov_b32_e32 v14, v23
	v_mov_b32_e32 v22, v20
	v_mov_b32_e32 v23, v12
	v_mov_b32_e32 v12, v21
	v_lshl_add_u64 v[20:21], v[42:43], 1, s[6:7]
	v_or_b32_e32 v42, s54, v2
	v_mov_b32_e32 v43, s10
	v_lshlrev_b64 v[42:43], 11, v[42:43]
	v_lshl_add_u64 v[46:47], v[20:21], 0, v[42:43]
	v_or_b32_e32 v48, 0x800, v42
	v_mov_b32_e32 v49, v43
	v_or_b32_e32 v50, 0x1000, v42
	v_mov_b32_e32 v51, v43
	v_or_b32_e32 v42, 0x1800, v42
	v_lshl_add_u64 v[48:49], v[20:21], 0, v[48:49]
	v_lshl_add_u64 v[50:51], v[20:21], 0, v[50:51]
	v_lshl_add_u64 v[20:21], v[20:21], 0, v[42:43]
	s_add_i32 s53, s53, s9
	s_cmpk_gt_i32 s53, 0xff
	s_waitcnt vmcnt(0)
	v_mov_b32_e32 v38, v120
	v_mov_b32_e32 v39, v121
	v_mov_b32_e32 v40, v122
	v_mov_b32_e32 v41, v123
	v_mov_b32_e32 v42, v39
	v_mov_b32_e32 v43, v40
	v_fma_mixlo_f16 v37, v10, v38, 0
	v_fma_mixlo_f16 v39, v11, v38, 0
	v_fma_mixlo_f16 v40, v8, v38, 0
	v_fma_mixlo_f16 v38, v9, v38, 0
	v_pk_mul_f32 v[8:9], v[44:45], v[42:43]
	v_fma_mixlo_f16 v18, v18, v41, 0
	v_pk_mul_f32 v[10:11], v[14:15], v[42:43]
	v_pk_mul_f32 v[14:15], v[22:23], v[42:43]
	v_pk_mul_f32 v[12:13], v[12:13], v[42:43]
	v_cvt_pk_f16_f32 v9, v8, v9
	v_fma_mixlo_f16 v19, v19, v41, 0
	v_fma_mixlo_f16 v16, v16, v41, 0
	v_fma_mixlo_f16 v17, v17, v41, 0
	v_cvt_pk_f16_f32 v11, v10, v11
	v_cvt_pk_f16_f32 v14, v14, v15
	v_cvt_pk_f16_f32 v15, v12, v13
	v_pack_b32_f16 v8, v37, v9
	v_alignbit_b32 v9, v18, v9, 16
	v_pack_b32_f16 v10, v39, v11
	v_alignbit_b32 v11, v19, v11, 16
	v_pack_b32_f16 v12, v40, v14
	v_alignbit_b32 v13, v16, v14, 16
	v_pack_b32_f16 v14, v38, v15
	v_alignbit_b32 v15, v17, v15, 16
	global_store_dwordx2 v[46:47], v[8:9], off
	global_store_dwordx2 v[48:49], v[10:11], off
	global_store_dwordx2 v[50:51], v[12:13], off
	global_store_dwordx2 v[20:21], v[14:15], off
	v_add_u32_e32 v0, 0x100, v0
	v_mov_b32_e32 v8, v0
	v_lshlrev_b32_e32 v10, 4, v8
	s_load_dword s9, s[0:1], 0x60
	s_add_u32 s6, s40, 0x1fb00000
	v_lshlrev_b32_e32 v1, 1, v8
	v_and_b32_e32 v2, 0x90, v10
	s_movk_i32 s3, 0x6c
	v_lshlrev_b32_e32 v3, 3, v8
	v_ashrrev_i32_e32 v9, 31, v8
	s_addc_u32 s7, s41, 0
	v_and_or_b32 v2, v1, s3, v2
	v_ashrrev_i32_e32 v11, 6, v8
	v_ashrrev_i32_e32 v1, 4, v8
	v_and_b32_e32 v4, 0x78, v3
	v_lshl_add_u64 v[6:7], v[8:9], 4, s[40:41]
	s_mov_b64 s[4:5], 0x20a00000
	v_and_b32_e32 v8, 63, v8
	v_lshl_add_u64 v[6:7], v[6:7], 0, s[4:5]
	v_lshlrev_b32_e32 v3, 9, v1
	v_lshlrev_b32_e32 v9, 2, v4
	v_add_u32_e32 v24, 0, v10
	s_add_u32 s4, s0, 0x60
	v_lshl_add_u32 v8, v8, 4, 0
	v_mov_b32_e32 v5, 0
	s_mov_b32 s11, 0
	v_add3_u32 v3, 0, v3, v9
	s_movk_i32 s3, 0x4000
	v_add_u32_e32 v25, 0x4000, v24
	v_lshl_add_u32 v26, v11, 11, 0
	v_lshlrev_b32_e32 v27, 2, v11
	s_addc_u32 s5, s1, 0
	s_mov_b32 s14, 0x14000
	v_add_u32_e32 v28, 0x14000, v24
	s_mov_b32 s15, 0x16000
	v_add_u32_e32 v29, 0x16000, v24
	s_mov_b32 s33, 0x18000
	v_add_u32_e32 v30, 0x18000, v24
	s_mov_b32 s34, 0x1a000
	v_add_u32_e32 v31, 0x1a000, v24
	s_mov_b32 s35, 0x1c000
	v_add_u32_e32 v32, 0x1c000, v24
	s_mov_b32 s36, 0x1e000
	v_add_u32_e32 v33, 0x1e000, v24
	v_add_u32_e32 v34, 0x20000, v24
	v_add_u32_e32 v35, 0x22000, v24
	v_add_u32_e32 v36, 0x4000, v8
	s_movk_i32 s37, 0x2400
	s_movk_i32 s44, 0x2000
	s_movk_i32 s45, 0x6000
	s_mov_b32 s46, 0x8000
	s_mov_b32 s47, 0xa000
	s_mov_b32 s48, 0xc000
	s_mov_b32 s49, 0xe000
	s_mov_b32 s50, 0x10000
	s_mov_b32 s51, 0x12000
	v_lshlrev_b32_e32 v4, 2, v4
	s_mov_b64 s[12:13], 0x1400
	s_movk_i32 s52, 0x1000
	s_mov_b32 s53, s2
	s_ashr_i32 s55, s53, 7
	s_bfe_u32 s54, s53, 0x20005
	s_mul_i32 s56, s55, 0x900000
	s_mul_hi_i32 s10, s55, 0x900000
	s_add_u32 s58, s22, s56
	s_addc_u32 s59, s23, s10
	s_lshl_b32 s10, s53, 5
	s_and_b32 s56, s10, 0x3e0
	v_add_u32_e32 v10, s56, v1
	v_mov_b64_e32 v[8:9], s[58:59]
	v_mad_i64_i32 v[8:9], s[58:59], v10, s37, v[8:9]
	s_lshl_b32 s10, s54, 9
	v_lshl_add_u64 v[8:9], v[8:9], 0, s[10:11]
	s_lshl_b32 s10, s55, 2
	s_or_b32 s58, s10, s54
	v_lshl_add_u64 v[8:9], v[8:9], 0, v[4:5]
	s_ashr_i32 s59, s58, 31
	v_add_co_u32_e32 v10, vcc, s52, v8
	s_lshl_b64 s[58:59], s[58:59], 17
	s_nop 0
	v_addc_co_u32_e32 v11, vcc, 0, v9, vcc
	v_lshl_add_u64 v[86:87], v[6:7], 0, s[58:59]
	v_add_co_u32_e32 v20, vcc, s44, v86
	v_lshl_add_u64 v[12:13], v[8:9], 0, s[12:13]
	s_nop 0
	v_addc_co_u32_e32 v21, vcc, 0, v87, vcc
	v_add_co_u32_e32 v38, vcc, s3, v86
	s_waitcnt lgkmcnt(0)
	s_nop 0
	v_addc_co_u32_e32 v39, vcc, 0, v87, vcc
	v_add_co_u32_e32 v42, vcc, s45, v86
	s_nop 0
	v_addc_co_u32_e32 v43, vcc, 0, v87, vcc
	v_add_co_u32_e32 v46, vcc, s46, v86
	s_nop 1
	v_addc_co_u32_e32 v47, vcc, 0, v87, vcc
	v_add_co_u32_e32 v50, vcc, s47, v86
	s_nop 0
	v_addc_co_u32_e32 v51, vcc, 0, v87, vcc
	v_add_co_u32_e32 v54, vcc, s48, v86
	s_nop 0
	v_addc_co_u32_e32 v55, vcc, 0, v87, vcc
	v_add_co_u32_e32 v58, vcc, s49, v86
	s_nop 0
	v_addc_co_u32_e32 v59, vcc, 0, v87, vcc
	v_add_co_u32_e32 v62, vcc, s50, v86
	s_nop 0
	v_addc_co_u32_e32 v63, vcc, 0, v87, vcc
	v_add_co_u32_e32 v66, vcc, s51, v86
	s_mov_b32 s10, -4
	s_nop 0
	v_addc_co_u32_e32 v67, vcc, 0, v87, vcc
	v_add_co_u32_e32 v70, vcc, s14, v86
	v_mov_b32_e32 v37, v26
	s_nop 0
	v_addc_co_u32_e32 v71, vcc, 0, v87, vcc
	v_add_co_u32_e32 v74, vcc, s15, v86
	s_nop 1
	v_addc_co_u32_e32 v75, vcc, 0, v87, vcc
	v_add_co_u32_e32 v78, vcc, s33, v86
	s_nop 0
	s_nop 0
	s_nop 0
	s_nop 0
	s_nop 0
	v_addc_co_u32_e32 v79, vcc, 0, v87, vcc
	v_add_co_u32_e32 v82, vcc, s34, v86
	s_nop 1
	v_addc_co_u32_e32 v83, vcc, 0, v87, vcc
	v_add_co_u32_e32 v88, vcc, s35, v86
	s_nop 0
	v_addc_co_u32_e32 v89, vcc, 0, v87, vcc
	v_add_co_u32_e32 v90, vcc, s36, v86
	s_nop 1
	v_addc_co_u32_e32 v91, vcc, 0, v87, vcc
	s_nop 0
	s_waitcnt vmcnt(0)
	v_mov_b32_e32 v38, v36
	v_mov_b32_e32 v10, 0
	v_mov_b32_e32 v11, v5
	v_mov_b32_e32 v8, 0
	v_mov_b32_e32 v9, v5
	v_mov_b32_e32 v22, 0
	v_mov_b32_e32 v23, v5
	v_mov_b32_e32 v20, 0
	v_mov_b32_e32 v21, v5
	v_mov_b32_e32 v14, 0
	v_mov_b32_e32 v15, v5
	v_mov_b32_e32 v12, 0
	v_mov_b32_e32 v13, v5
	v_mov_b32_e32 v18, 0
	v_mov_b32_e32 v19, v5
	v_mov_b32_e32 v16, 0
	v_mov_b32_e32 v17, v5
	v_add_u32_e32 v124, s56, v27
	s_lshl_b32 s58, s55, 10
	s_ashr_i32 s59, s58, 31
	s_lshl_b64 s[58:59], s[58:59], 2
	s_add_u32 s58, s20, s58
	s_addc_u32 s59, s21, s59
	v_ashrrev_i32_e32 v125, 31, v124
	v_lshl_add_u64 v[126:127], v[124:125], 2, s[58:59]
	global_load_dwordx4 v[120:123], v[126:127], off
; #define LAS __attribute__((address_space(3)))
; __device__ void p_weights_prod(const Args& a, LAS unsigned char* lds) {
;     ...
; #pragma unroll 2
;         for (int c0 = 0; c0 < 128; c0 += 4) {
;             f32x4 w4[4], m4[4];
; #pragma unroll
;             for (int r2 = 0; r2 < 4; ++r2) w4[r2] = *(const LAS f32x4*)(wt + (4 * rq + r2) * 128 + c0);
; #pragma unroll
;             for (int cc = 0; cc < 4; ++cc) m4[cc] = *(const LAS f32x4*)(mmt + (c0 + cc) * 256 + lc0);
; #pragma unroll
;             for (int r2 = 0; r2 < 4; ++r2)
; #pragma unroll
;                 for (int cc = 0; cc < 4; ++cc) acc[r2] += m4[cc] * w4[r2][cc];
;         }
.Lpw_kb:
	ds_read_b128 v[40:43], v38
	ds_read_b128 v[44:47], v38 offset:1024
	ds_read_b128 v[48:51], v38 offset:2048
	ds_read_b128 v[52:55], v38 offset:3072
	ds_read_b128 v[56:59], v37
	ds_read_b128 v[60:63], v37 offset:16
	ds_read_b128 v[64:67], v37 offset:512
	ds_read_b128 v[68:71], v37 offset:528
	ds_read_b128 v[72:75], v37 offset:1024
	ds_read_b128 v[76:79], v37 offset:1040
	ds_read_b128 v[80:83], v37 offset:1536
	ds_read_b128 v[84:87], v37 offset:1552
	ds_read_b128 v[88:91], v38 offset:4096
	ds_read_b128 v[92:95], v38 offset:5120
	ds_read_b128 v[96:99], v38 offset:6144
	ds_read_b128 v[100:103], v38 offset:7168
	s_waitcnt lgkmcnt(11)
	v_pk_fma_f32 v[8:9], v[56:57], v[42:43], v[8:9] op_sel_hi:[0,1,1]
	v_pk_fma_f32 v[10:11], v[56:57], v[40:41], v[10:11] op_sel_hi:[0,1,1]
	s_waitcnt lgkmcnt(9)
	v_pk_fma_f32 v[20:21], v[64:65], v[42:43], v[20:21] op_sel_hi:[0,1,1]
	v_pk_fma_f32 v[22:23], v[64:65], v[40:41], v[22:23] op_sel_hi:[0,1,1]
	s_waitcnt lgkmcnt(7)
	v_pk_fma_f32 v[12:13], v[72:73], v[42:43], v[12:13] op_sel_hi:[0,1,1]
	v_pk_fma_f32 v[14:15], v[72:73], v[40:41], v[14:15] op_sel_hi:[0,1,1]
	s_waitcnt lgkmcnt(5)
	v_pk_fma_f32 v[16:17], v[42:43], v[80:81], v[16:17] op_sel_hi:[1,0,1]
	v_pk_fma_f32 v[18:19], v[40:41], v[80:81], v[18:19] op_sel_hi:[1,0,1]
	v_pk_fma_f32 v[8:9], v[56:57], v[46:47], v[8:9] op_sel:[1,0,0]
	v_pk_fma_f32 v[10:11], v[56:57], v[44:45], v[10:11] op_sel:[1,0,0]
	v_pk_fma_f32 v[20:21], v[64:65], v[46:47], v[20:21] op_sel:[1,0,0]
	v_pk_fma_f32 v[22:23], v[64:65], v[44:45], v[22:23] op_sel:[1,0,0]
	v_pk_fma_f32 v[12:13], v[72:73], v[46:47], v[12:13] op_sel:[1,0,0]
	v_pk_fma_f32 v[14:15], v[72:73], v[44:45], v[14:15] op_sel:[1,0,0]
	v_pk_fma_f32 v[16:17], v[80:81], v[46:47], v[16:17] op_sel:[1,0,0]
	v_pk_fma_f32 v[18:19], v[80:81], v[44:45], v[18:19] op_sel:[1,0,0]
	v_mov_b32_e32 v40, v59
	v_mov_b32_e32 v42, v67
	v_mov_b32_e32 v104, v75
	v_mov_b32_e32 v106, v83
	v_pk_fma_f32 v[10:11], v[58:59], v[48:49], v[10:11] op_sel_hi:[0,1,1]
	v_pk_fma_f32 v[8:9], v[58:59], v[50:51], v[8:9] op_sel_hi:[0,1,1]
	v_pk_fma_f32 v[22:23], v[66:67], v[48:49], v[22:23] op_sel_hi:[0,1,1]
	v_pk_fma_f32 v[20:21], v[66:67], v[50:51], v[20:21] op_sel_hi:[0,1,1]
	v_pk_fma_f32 v[14:15], v[74:75], v[48:49], v[14:15] op_sel_hi:[0,1,1]
	v_pk_fma_f32 v[12:13], v[74:75], v[50:51], v[12:13] op_sel_hi:[0,1,1]
	v_pk_fma_f32 v[18:19], v[82:83], v[48:49], v[18:19] op_sel_hi:[0,1,1]
	v_pk_fma_f32 v[16:17], v[82:83], v[50:51], v[16:17] op_sel_hi:[0,1,1]
	v_pk_fma_f32 v[8:9], v[40:41], v[54:55], v[8:9] op_sel_hi:[0,1,1]
	v_pk_fma_f32 v[10:11], v[40:41], v[52:53], v[10:11] op_sel_hi:[0,1,1]
	v_pk_fma_f32 v[20:21], v[42:43], v[54:55], v[20:21] op_sel_hi:[0,1,1]
	v_pk_fma_f32 v[22:23], v[42:43], v[52:53], v[22:23] op_sel_hi:[0,1,1]
	v_pk_fma_f32 v[12:13], v[104:105], v[54:55], v[12:13] op_sel_hi:[0,1,1]
	v_pk_fma_f32 v[14:15], v[104:105], v[52:53], v[14:15] op_sel_hi:[0,1,1]
	v_pk_fma_f32 v[16:17], v[106:107], v[54:55], v[16:17] op_sel_hi:[0,1,1]
	v_pk_fma_f32 v[18:19], v[106:107], v[52:53], v[18:19] op_sel_hi:[0,1,1]
	s_waitcnt lgkmcnt(3)
	v_pk_fma_f32 v[10:11], v[60:61], v[88:89], v[10:11] op_sel_hi:[0,1,1]
	v_pk_fma_f32 v[8:9], v[60:61], v[90:91], v[8:9] op_sel_hi:[0,1,1]
	v_pk_fma_f32 v[22:23], v[68:69], v[88:89], v[22:23] op_sel_hi:[0,1,1]
	v_pk_fma_f32 v[20:21], v[68:69], v[90:91], v[20:21] op_sel_hi:[0,1,1]
	v_pk_fma_f32 v[14:15], v[76:77], v[88:89], v[14:15] op_sel_hi:[0,1,1]
	v_pk_fma_f32 v[12:13], v[76:77], v[90:91], v[12:13] op_sel_hi:[0,1,1]
	v_pk_fma_f32 v[18:19], v[88:89], v[84:85], v[18:19] op_sel_hi:[1,0,1]
	v_pk_fma_f32 v[16:17], v[90:91], v[84:85], v[16:17] op_sel_hi:[1,0,1]
	s_waitcnt lgkmcnt(2)
	v_pk_fma_f32 v[8:9], v[60:61], v[94:95], v[8:9] op_sel:[1,0,0]
	v_pk_fma_f32 v[10:11], v[60:61], v[92:93], v[10:11] op_sel:[1,0,0]
	v_pk_fma_f32 v[20:21], v[68:69], v[94:95], v[20:21] op_sel:[1,0,0]
	v_pk_fma_f32 v[22:23], v[68:69], v[92:93], v[22:23] op_sel:[1,0,0]
	v_pk_fma_f32 v[12:13], v[76:77], v[94:95], v[12:13] op_sel:[1,0,0]
	v_pk_fma_f32 v[14:15], v[76:77], v[92:93], v[14:15] op_sel:[1,0,0]
	v_pk_fma_f32 v[16:17], v[84:85], v[94:95], v[16:17] op_sel:[1,0,0]
	v_pk_fma_f32 v[18:19], v[84:85], v[92:93], v[18:19] op_sel:[1,0,0]
	s_add_i32 s10, s10, 8
	v_mov_b32_e32 v108, v63
	v_mov_b32_e32 v110, v71
	v_mov_b32_e32 v112, v79
	v_mov_b32_e32 v114, v87
	s_waitcnt lgkmcnt(1)
	v_pk_fma_f32 v[10:11], v[62:63], v[96:97], v[10:11] op_sel_hi:[0,1,1]
	v_pk_fma_f32 v[8:9], v[62:63], v[98:99], v[8:9] op_sel_hi:[0,1,1]
	v_pk_fma_f32 v[22:23], v[70:71], v[96:97], v[22:23] op_sel_hi:[0,1,1]
	v_pk_fma_f32 v[20:21], v[70:71], v[98:99], v[20:21] op_sel_hi:[0,1,1]
	v_pk_fma_f32 v[14:15], v[78:79], v[96:97], v[14:15] op_sel_hi:[0,1,1]
	v_pk_fma_f32 v[12:13], v[78:79], v[98:99], v[12:13] op_sel_hi:[0,1,1]
	v_pk_fma_f32 v[18:19], v[86:87], v[96:97], v[18:19] op_sel_hi:[0,1,1]
	v_pk_fma_f32 v[16:17], v[86:87], v[98:99], v[16:17] op_sel_hi:[0,1,1]
	v_add_u32_e32 v38, 0x2000, v38
	v_add_u32_e32 v37, 32, v37
	s_cmpk_gt_u32 s10, 0x7b
	s_waitcnt lgkmcnt(0)
	v_pk_fma_f32 v[8:9], v[108:109], v[102:103], v[8:9] op_sel_hi:[0,1,1]
	v_pk_fma_f32 v[10:11], v[108:109], v[100:101], v[10:11] op_sel_hi:[0,1,1]
	v_pk_fma_f32 v[20:21], v[110:111], v[102:103], v[20:21] op_sel_hi:[0,1,1]
	v_pk_fma_f32 v[22:23], v[110:111], v[100:101], v[22:23] op_sel_hi:[0,1,1]
	v_pk_fma_f32 v[12:13], v[112:113], v[102:103], v[12:13] op_sel_hi:[0,1,1]
	v_pk_fma_f32 v[14:15], v[112:113], v[100:101], v[14:15] op_sel_hi:[0,1,1]
	v_pk_fma_f32 v[16:17], v[114:115], v[102:103], v[16:17] op_sel_hi:[0,1,1]
	v_pk_fma_f32 v[18:19], v[114:115], v[100:101], v[18:19] op_sel_hi:[0,1,1]
	s_cbranch_scc0 .Lpw_kb
; __device__ void p_weights_prod(const Args& a, LAS unsigned char* lds) {
;     ...
;         const int k0 = kblk * 32 + 4 * rq;
;         const f32x4 gn = *(const f32x4*)(a.norm_gain + l * DM + k0);
; #pragma unroll
;         for (int j = 0; j < 4; ++j) {
;             f16x4 o;
; #pragma unroll
;             for (int r2 = 0; r2 < 4; ++r2) o[r2] = (f16)(acc[r2][j] * gn[r2]);
;             *(f16x4*)(W1T + ((size_t)l * N1 + pn * 256 + rho0 + j) * 1024 + k0) = o;
;         }
;     }
;     __syncthreads();
	v_add_u32_e32 v42, s56, v27
	s_lshl_b32 s56, s55, 10
	s_ashr_i32 s57, s56, 31
	s_lshl_b64 s[56:57], s[56:57], 2
	s_add_u32 s56, s20, s56
	s_addc_u32 s57, s21, s57
	v_ashrrev_i32_e32 v43, 31, v42
	s_lshl_b32 s54, s54, 8
	s_mul_hi_i32 s10, s55, 0xb00
	s_mulk_i32 s55, 0xb00
	s_addk_i32 s54, 0x700
	s_add_u32 s54, s55, s54
	s_addc_u32 s10, s10, 0
	v_mov_b32_e32 v44, v22
	v_mov_b32_e32 v45, v14
	v_mov_b32_e32 v14, v23
	v_mov_b32_e32 v22, v20
	v_mov_b32_e32 v23, v12
	v_mov_b32_e32 v12, v21
	v_lshl_add_u64 v[20:21], v[42:43], 1, s[6:7]
	v_or_b32_e32 v42, s54, v2
	v_mov_b32_e32 v43, s10
	v_lshlrev_b64 v[42:43], 11, v[42:43]
	v_lshl_add_u64 v[46:47], v[20:21], 0, v[42:43]
	v_or_b32_e32 v48, 0x800, v42
	v_mov_b32_e32 v49, v43
	v_or_b32_e32 v50, 0x1000, v42
	v_mov_b32_e32 v51, v43
	v_or_b32_e32 v42, 0x1800, v42
	v_lshl_add_u64 v[48:49], v[20:21], 0, v[48:49]
	v_lshl_add_u64 v[50:51], v[20:21], 0, v[50:51]
	v_lshl_add_u64 v[20:21], v[20:21], 0, v[42:43]
	s_add_i32 s53, s53, s9
	s_cmpk_gt_i32 s53, 0xff
	s_waitcnt vmcnt(0)
	v_mov_b32_e32 v38, v120
	v_mov_b32_e32 v39, v121
	v_mov_b32_e32 v40, v122
	v_mov_b32_e32 v41, v123
	v_mov_b32_e32 v42, v39
	v_mov_b32_e32 v43, v40
	v_fma_mixlo_f16 v37, v10, v38, 0
	v_fma_mixlo_f16 v39, v11, v38, 0
	v_fma_mixlo_f16 v40, v8, v38, 0
	v_fma_mixlo_f16 v38, v9, v38, 0
	v_pk_mul_f32 v[8:9], v[44:45], v[42:43]
	v_fma_mixlo_f16 v18, v18, v41, 0
	v_pk_mul_f32 v[10:11], v[14:15], v[42:43]
	v_pk_mul_f32 v[14:15], v[22:23], v[42:43]
	v_pk_mul_f32 v[12:13], v[12:13], v[42:43]
	v_cvt_pk_f16_f32 v9, v8, v9
	v_fma_mixlo_f16 v19, v19, v41, 0
	v_fma_mixlo_f16 v16, v16, v41, 0
	v_fma_mixlo_f16 v17, v17, v41, 0
	v_cvt_pk_f16_f32 v11, v10, v11
	v_cvt_pk_f16_f32 v14, v14, v15
	v_cvt_pk_f16_f32 v15, v12, v13
	v_pack_b32_f16 v8, v37, v9
	v_alignbit_b32 v9, v18, v9, 16
	v_pack_b32_f16 v10, v39, v11
	v_alignbit_b32 v11, v19, v11, 16
	v_pack_b32_f16 v12, v40, v14
	v_alignbit_b32 v13, v16, v14, 16
	v_pack_b32_f16 v14, v38, v15
	v_alignbit_b32 v15, v17, v15, 16
	global_store_dwordx2 v[46:47], v[8:9], off
	global_store_dwordx2 v[48:49], v[10:11], off
	global_store_dwordx2 v[50:51], v[12:13], off
	global_store_dwordx2 v[20:21], v[14:15], off
	v_add_u32_e32 v0, 0xffffff00, v0
	s_barrier
	s_branch .LBB0_112
